# GDN prep first item: raw rows fetched with 13 loads in flight on waves 4..7 (the S3 loader) instead of the seven-round-trip loop in S0
# baseline (speedup 1.0000x reference)
.LBB0_44:
	v_ashrrev_i32_e32 v2, 9, v46
	v_ashrrev_i32_e32 v3, 31, v2
	s_waitcnt lgkmcnt(0)
	s_barrier
	v_readlane_b32 s0, v254, 37
	v_and_b32_e32 v0, 63, v46
	v_bfe_u32 v7, v46, 6, 3
	v_lshlrev_b64 v[82:83], 12, v[2:3]
	v_readlane_b32 s1, v254, 38
	v_cmp_eq_u32_e32 vcc, s0, v46
	v_lshl_or_b32 v82, v0, 6, v82
	s_and_b64 s[0:1], s[6:7], vcc
	v_lshlrev_b32_e32 v84, 7, v7
	s_and_saveexec_b64 s[20:21], s[0:1]
	s_cbranch_execz .LBB0_63
	v_readfirstlane_b32 s26, v166
	s_bitcmp1_b32 s26, 8
	s_cbranch_scc0 .LBB0_63
	v_readfirstlane_b32 s26, v46
	s_and_b32 s27, s26, 63
	s_bfe_u32 s28, s26, 0x30006
	s_lshl_b32 s28, s28, 8
	s_lshr_b32 s29, s26, 9
	s_lshl_b32 s30, s29, 12
	s_lshl_b32 s31, s27, 6
	s_add_i32 s30, s30, s31
	s_add_i32 s30, s30, -3
	s_lshl_b32 s34, s30, 13
	s_ashr_i32 s35, s30, 31
	s_add_u32 s34, s34, s74
	s_addc_u32 s35, s35, s75
	s_add_u32 s34, s34, s28
	s_addc_u32 s35, s35, 0
	s_lshl_b32 s29, s29, 6
	s_add_i32 s29, s29, s27
	s_mul_i32 s29, s29, 0x4800
	s_add_i32 s29, s29, s28
	s_add_u32 s30, s82, s29
	s_addc_u32 s31, s83, 0
	s_mov_b32 s26, 0xaaaaaaab
	v_add_u32_e32 v202, 0xffffff00, v166
	v_mul_hi_u32 v204, v202, s26
	v_lshrrev_b32_e32 v204, 5, v204
	v_mul_u32_u24_e32 v220, 48, v204
	v_sub_u32_e32 v220, v202, v220
	v_lshrrev_b32_e32 v221, 4, v220
	v_mul_u32_u24_e32 v221, 0x700, v221
	v_lshl_add_u32 v221, v220, 4, v221
	v_mov_b32_e32 v190, 0
	v_mov_b32_e32 v191, 0
	v_mov_b32_e32 v192, 0
	v_mov_b32_e32 v193, 0
	s_mov_b64 s[28:29], exec
	v_cmp_gt_u32_e32 vcc, 3, v204
	s_and_b64 exec, s[28:29], vcc
	s_cbranch_execz .Lrl0_nohalo
	s_cmp_eq_u32 s27, 0
	s_cbranch_scc1 .Lrl0_nohalo
	v_mul_u32_u24_e32 v226, 0x1800, v204
	v_add_u32_e32 v226, v226, v221
	global_load_dwordx4 v[190:193], v226, s[30:31]

.Lrl0_noproj:
	s_mov_b64 exec, s[28:29]
	v_add_u32_e32 v203, 256, v202
	v_mul_hi_u32 v204, v203, s26
	v_lshrrev_b32_e32 v204, 5, v204
	v_mul_u32_u24_e32 v220, 48, v204
	v_sub_u32_e32 v220, v203, v220
	v_lshrrev_b32_e32 v221, 4, v220
	v_mul_u32_u24_e32 v221, 0x700, v221
	v_lshl_add_u32 v221, v220, 4, v221
	v_lshl_add_u32 v221, v204, 13, v221
	global_load_dwordx4 v[194:197], v221, s[34:35]
	v_add_u32_e32 v203, 512, v202
	v_mul_hi_u32 v204, v203, s26
	v_lshrrev_b32_e32 v204, 5, v204
	v_mul_u32_u24_e32 v220, 48, v204
	v_sub_u32_e32 v220, v203, v220
	v_lshrrev_b32_e32 v221, 4, v220
	v_mul_u32_u24_e32 v221, 0x700, v221
	v_lshl_add_u32 v221, v220, 4, v221
	v_lshl_add_u32 v221, v204, 13, v221
	global_load_dwordx4 v[198:201], v221, s[34:35]
	v_add_u32_e32 v203, 768, v202
	v_mul_hi_u32 v204, v203, s26
	v_lshrrev_b32_e32 v204, 5, v204
	v_mul_u32_u24_e32 v220, 48, v204
	v_sub_u32_e32 v220, v203, v220
	v_lshrrev_b32_e32 v221, 4, v220
	v_mul_u32_u24_e32 v221, 0x700, v221
	v_lshl_add_u32 v221, v220, 4, v221
	v_lshl_add_u32 v221, v204, 13, v221
	global_load_dwordx4 v[206:209], v221, s[34:35]
	v_add_u32_e32 v203, 1024, v202
	v_mul_hi_u32 v204, v203, s26
	v_lshrrev_b32_e32 v204, 5, v204
	v_mul_u32_u24_e32 v220, 48, v204
	v_sub_u32_e32 v220, v203, v220
	v_lshrrev_b32_e32 v221, 4, v220
	v_mul_u32_u24_e32 v221, 0x700, v221
	v_lshl_add_u32 v221, v220, 4, v221
	v_lshl_add_u32 v221, v204, 13, v221
	global_load_dwordx4 v[210:213], v221, s[34:35]
	v_add_u32_e32 v203, 1280, v202
	v_mul_hi_u32 v204, v203, s26
	v_lshrrev_b32_e32 v204, 5, v204
	v_mul_u32_u24_e32 v220, 48, v204
	v_sub_u32_e32 v220, v203, v220
	v_lshrrev_b32_e32 v221, 4, v220
	v_mul_u32_u24_e32 v221, 0x700, v221
	v_lshl_add_u32 v221, v220, 4, v221
	v_lshl_add_u32 v221, v204, 13, v221
	global_load_dwordx4 v[214:217], v221, s[34:35]
	v_add_u32_e32 v203, 1536, v202
	v_mul_hi_u32 v204, v203, s26
	v_lshrrev_b32_e32 v204, 5, v204
	v_mul_u32_u24_e32 v220, 48, v204
	v_sub_u32_e32 v220, v203, v220
	v_lshrrev_b32_e32 v221, 4, v220
	v_mul_u32_u24_e32 v221, 0x700, v221
	v_lshl_add_u32 v221, v220, 4, v221
	v_lshl_add_u32 v221, v204, 13, v221
	global_load_dwordx4 v[238:241], v221, s[34:35]
	v_add_u32_e32 v203, 1792, v202
	v_mul_hi_u32 v204, v203, s26
	v_lshrrev_b32_e32 v204, 5, v204
	v_mul_u32_u24_e32 v220, 48, v204
	v_sub_u32_e32 v220, v203, v220
	v_lshrrev_b32_e32 v221, 4, v220
	v_mul_u32_u24_e32 v221, 0x700, v221
	v_lshl_add_u32 v221, v220, 4, v221
	v_lshl_add_u32 v221, v204, 13, v221
	global_load_dwordx4 v[242:245], v221, s[34:35]
	v_add_u32_e32 v203, 2048, v202
	v_mul_hi_u32 v204, v203, s26
	v_lshrrev_b32_e32 v204, 5, v204
	v_mul_u32_u24_e32 v220, 48, v204
	v_sub_u32_e32 v220, v203, v220
	v_lshrrev_b32_e32 v221, 4, v220
	v_mul_u32_u24_e32 v221, 0x700, v221
	v_lshl_add_u32 v221, v220, 4, v221
	v_lshl_add_u32 v221, v204, 13, v221
	global_load_dwordx4 v[246:249], v221, s[34:35]
	v_add_u32_e32 v203, 2304, v202
	v_mul_hi_u32 v204, v203, s26
	v_lshrrev_b32_e32 v204, 5, v204
	v_mul_u32_u24_e32 v220, 48, v204
	v_sub_u32_e32 v220, v203, v220
	v_lshrrev_b32_e32 v221, 4, v220
	v_mul_u32_u24_e32 v221, 0x700, v221
	v_lshl_add_u32 v221, v220, 4, v221
	v_lshl_add_u32 v221, v204, 13, v221
	global_load_dwordx4 v[88:91], v221, s[34:35]
	v_add_u32_e32 v203, 2560, v202
	v_mul_hi_u32 v204, v203, s26
	v_lshrrev_b32_e32 v204, 5, v204
	v_mul_u32_u24_e32 v220, 48, v204
	v_sub_u32_e32 v220, v203, v220
	v_lshrrev_b32_e32 v221, 4, v220
	v_mul_u32_u24_e32 v221, 0x700, v221
	v_lshl_add_u32 v221, v220, 4, v221
	v_lshl_add_u32 v221, v204, 13, v221
	global_load_dwordx4 v[92:95], v221, s[34:35]
	v_add_u32_e32 v203, 2816, v202
	v_mul_hi_u32 v204, v203, s26
	v_lshrrev_b32_e32 v204, 5, v204
	v_mul_u32_u24_e32 v220, 48, v204
	v_sub_u32_e32 v220, v203, v220
	v_lshrrev_b32_e32 v221, 4, v220
	v_mul_u32_u24_e32 v221, 0x700, v221
	v_lshl_add_u32 v221, v220, 4, v221
	v_lshl_add_u32 v221, v204, 13, v221
	global_load_dwordx4 v[96:99], v221, s[34:35]
	v_cmp_gt_u32_e32 vcc, 0x90, v202
	s_and_b64 exec, s[28:29], vcc
	s_cbranch_execz .Lrl0_no12
	v_add_u32_e32 v203, 3072, v202
	v_mul_hi_u32 v204, v203, s26
	v_lshrrev_b32_e32 v204, 5, v204
	v_mul_u32_u24_e32 v220, 48, v204
	v_sub_u32_e32 v220, v203, v220
	v_lshrrev_b32_e32 v221, 4, v220
	v_mul_u32_u24_e32 v221, 0x700, v221
	v_lshl_add_u32 v221, v220, 4, v221
	v_lshl_add_u32 v221, v204, 13, v221
	global_load_dwordx4 v[100:103], v221, s[34:35]
.Lrl0_no12:
	s_mov_b64 exec, s[28:29]
	v_lshlrev_b32_e32 v227, 4, v202
	s_waitcnt vmcnt(0)
	ds_write_b128 v227, v[190:193]
	ds_write_b128 v227, v[194:197] offset:4096
	ds_write_b128 v227, v[198:201] offset:8192
	ds_write_b128 v227, v[206:209] offset:12288
	ds_write_b128 v227, v[210:213] offset:16384
	ds_write_b128 v227, v[214:217] offset:20480
	ds_write_b128 v227, v[238:241] offset:24576
	ds_write_b128 v227, v[242:245] offset:28672
	ds_write_b128 v227, v[246:249] offset:32768
	ds_write_b128 v227, v[88:91] offset:36864
	ds_write_b128 v227, v[92:95] offset:40960
	ds_write_b128 v227, v[96:99] offset:45056
	v_cmp_gt_u32_e32 vcc, 0x90, v202
	s_and_b64 exec, s[28:29], vcc
	s_cbranch_execz .Lrl0_now12
	ds_write_b128 v227, v[100:103] offset:49152
.Lrl0_now12:
	s_mov_b64 exec, s[28:29]
.LBB0_63:
	s_or_b64 exec, exec, s[20:21]
	s_and_saveexec_b64 s[0:1], s[8:9]
	s_cbranch_execz .LBB0_65
	v_lshl_add_u64 v[2:3], v[82:83], 0, v[166:167]
	v_lshlrev_b64 v[2:3], 6, v[2:3]
	v_lshl_add_u64 v[2:3], s[68:69], 0, v[2:3]
	v_lshlrev_b32_e32 v0, 2, v7
	v_lshl_add_u64 v[2:3], v[2:3], 0, v[0:1]
	global_load_dword v4, v[2:3], off
	global_load_dword v5, v0, s[12:13]
	s_nop 0
	global_load_dword v0, v0, s[10:11]
	s_nop 0
	global_load_dword v2, v[2:3], off offset:32
	s_mov_b32 s18, 0x800000
	v_mov_b32_e32 v3, v222
	v_mov_b32_e32 v6, v222
	v_lshl_add_u32 v3, v3, 2, -4
	v_mov_b32_e32 v7, v222
	v_lshl_add_u32 v6, v6, 2, -8
	v_mov_b32_e32 v8, v222
	v_mov_b32_e32 v9, v222
	v_mov_b32_e32 v10, v222
	s_waitcnt vmcnt(0) lgkmcnt(0)
	v_add_f32_e32 v4, v4, v5
	v_mul_f32_e32 v5, 0x3fb8aa3b, v4
	v_exp_f32_e32 v5, v5
	v_mul_f32_e32 v0, 0x3fb8aa3b, v0
	v_exp_f32_e32 v0, v0
	v_mul_f32_e32 v2, 0xbfb8aa3b, v2
	v_add_f32_e32 v5, 1.0, v5
	v_cmp_gt_f32_e32 vcc, s18, v5
	s_mov_b32 s18, 0x3f317217
	v_exp_f32_e32 v2, v2
	v_cndmask_b32_e64 v11, 0, 32, vcc
	v_ldexp_f32 v5, v5, v11
	v_log_f32_e32 v5, v5
	v_mov_b32_e32 v11, 0x41b17218
	v_cndmask_b32_e32 v11, 0, v11, vcc
	v_add_f32_e32 v2, 1.0, v2
	v_mul_f32_e32 v12, 0x3f317217, v5
	v_fma_f32 v12, v5, s18, -v12
	v_fmac_f32_e32 v12, 0x3377d1cf, v5
	s_mov_b32 s18, 0x7f800000
	v_fmac_f32_e32 v12, 0x3f317217, v5
	v_cmp_lt_f32_e64 vcc, |v5|, s18
	s_mov_b32 s18, 0x41a00000
	s_nop 0
	v_cndmask_b32_e32 v5, v5, v12, vcc
	v_sub_f32_e32 v5, v5, v11
	v_cmp_lt_f32_e32 vcc, s18, v4
	s_nop 1
	v_cndmask_b32_e32 v4, v5, v4, vcc
	v_mul_f32_e64 v5, v4, -v0
	ds_bpermute_b32 v3, v3, v5
	s_waitcnt lgkmcnt(0)
	v_fma_f32 v0, v4, -v0, v3
	v_cndmask_b32_e64 v0, v0, v5, s[42:43]
	ds_bpermute_b32 v3, v6, v0
	v_lshl_add_u32 v4, v7, 2, -16
	v_not_b32_e32 v5, 31
	v_lshl_add_u32 v5, v8, 2, v5
	v_lshl_add_u32 v6, v10, 2, v225
	s_waitcnt lgkmcnt(0)
	v_add_f32_e32 v3, v0, v3
	v_cndmask_b32_e64 v0, v3, v0, s[44:45]
	ds_bpermute_b32 v3, v4, v0
	v_lshl_add_u32 v4, v9, 2, v224
	s_waitcnt lgkmcnt(0)
	v_add_f32_e32 v3, v0, v3
	v_cndmask_b32_e64 v0, v3, v0, s[46:47]
	ds_bpermute_b32 v3, v5, v0
	v_div_scale_f32 v5, s[18:19], v2, v2, 1.0
	v_rcp_f32_e32 v7, v5
	s_waitcnt lgkmcnt(0)
	v_add_f32_e32 v3, v0, v3
	v_cndmask_b32_e64 v0, v3, v0, s[48:49]
	ds_bpermute_b32 v3, v4, v0
	v_fma_f32 v8, -v5, v7, 1.0
	v_div_scale_f32 v4, vcc, 1.0, v2, 1.0
	v_fmac_f32_e32 v7, v8, v7
	s_waitcnt lgkmcnt(0)
	v_add_f32_e32 v3, v0, v3
	v_cndmask_b32_e64 v0, v3, v0, s[50:51]
	ds_bpermute_b32 v3, v6, v0
	v_mul_f32_e32 v6, v4, v7
	v_fma_f32 v8, -v5, v6, v4
	v_fmac_f32_e32 v6, v8, v7
	v_fma_f32 v4, -v5, v6, v4
	s_waitcnt lgkmcnt(0)
	v_add_f32_e32 v3, v0, v3
	v_cndmask_b32_e64 v0, v3, v0, s[52:53]
	v_div_fmas_f32 v3, v4, v7, v6
	v_mul_f32_e32 v4, 0x3fb8aa3b, v0
	v_exp_f32_e32 v4, v4
	v_div_fixup_f32 v2, v3, v2, 1.0
	ds_write_b32 v114, v2
	ds_write2st64_b32 v41, v0, v2 offset1:2
	v_mul_f32_e32 v0, v2, v4
	ds_write_b32 v41, v0 offset:768
